# v17 + mixer-B row step: row mask via -inf LDS table address select, packed f32 adds for rpb add and l-sum
# speedup vs baseline: 1.0138x; 1.0007x over previous
; #define LAS __attribute__((address_space(3)))
; template <int MODE, bool FIX> ...
;     ...
;         head = rem >> 4; const int r0 = 4 * (rem & 15), rp = wid >> 2, cgp = wid & 3;
;         qrow = r0 + 2 * rp + (r32 >> 4); qc = 16 * cgp + (r32 & 15); qtok = qrow * 64 + qc; qcol = 768 + head * 64; kcol = 1280 + head * 64; vcol = 1792 + head * 64; ocol = 512 + head * 64;
;         kr_lo = (r0 - 4) > 0 ? (r0 - 4) : 0; const int kr_hi = clampi(r0 - 1, 0, 56) + 7; NTL = kr_hi - kr_lo + 1; lrow0 = b * SEQ + kr_lo * 64;
;         kc0 = clampi(16 * cgp - 8, 0, 32); const int cs = clampi(qc - 8, 0, 48);
;         wa_lo = clampi(r0 + 2 * rp - 4, 0, 56); wa_hi = clampi(r0 + 2 * rp - 3, 0, 56) + 7; rs = clampi(qrow - 4, 0, 56);
; #pragma unroll
;         for (int r = 0; r < 16; ++r) { const int kc = kc0 + (r & 3) + 8 * (r >> 2) + 4 * hi; if ((unsigned)(kc - cs) < 16u) colmask |= (1u << r); }
;         LAS float* rt = (LAS float*)(lds + RPB_OFF);
;         if (tid < 465) rt[tid] = rpb[head * 465 + tid] * LOG2E;
;     }
;     const int NT = NTL + 4, crow0 = ML + b * CTXL;
;     const LAS float* rpbl = (const LAS float*)(lds + RPB_OFF);
;     bf16x8 qf[4];
;     { const bf16_t* qp = QKV + (size_t)(b * SEQ + qtok) * INC + qcol + hi * 8;
; #pragma unroll
;       for (int d0 = 0; d0 < 4; ++d0) qf[d0] = *(const bf16x8*)(qp + d0 * 16); }
;     float m = FIX ? Mb : -INFINITY, l = 0.f;
;     const float ci = FIX ? -Mb : 0.f;
;     const f32x16 cinit = {ci, ci, ci, ci, ci, ci, ci, ci, ci, ci, ci, ci, ci, ci, ci, ci};
.LBB0_674:
	s_cmpk_eq_i32 s33, 0x100
	v_readlane_b32 s90, v255, 13
	s_cselect_b64 s[40:41], -1, 0
	v_readlane_b32 s1, v255, 19
	s_lshl_b32 s2, s90, 4
	s_lshl_b32 s0, s1, 2
	s_and_b32 s2, s2, 48
	s_and_b32 s0, s0, 0xffffff80
	s_and_b32 s1, s1, 31
	s_add_i32 s3, s2, -8
	v_and_b32_e32 v0, 15, v197
	s_or_b32 s0, s0, s1
	s_and_b32 s1, s85, 0x1fffffe
	s_min_u32 s3, s3, 32
	v_or_b32_e32 v149, s2, v0
	s_cmp_lg_u32 s2, 0
	v_subrev_co_u32_e32 v1, vcc, 8, v149
	s_cselect_b32 s3, s3, 0
	v_min_u32_e32 v2, 48, v1
	v_cndmask_b32_e64 v2, v2, 0, vcc
	v_add_u32_e32 v3, s3, v198
	v_sub_u32_e32 v2, v3, v2
	v_cmp_gt_u32_e32 vcc, 16, v2
	v_add_u32_e32 v4, 1, v2
	v_add_u32_e32 v5, 2, v2
	v_cndmask_b32_e64 v3, 0, 1, vcc
	v_cmp_gt_u32_e32 vcc, 16, v4
	v_add_u32_e32 v6, 3, v2
	v_add_u32_e32 v7, 8, v2
	v_cndmask_b32_e64 v4, 0, 2, vcc
	v_cmp_gt_u32_e32 vcc, 16, v5
	v_add_u32_e32 v8, 9, v2
	v_add_u32_e32 v9, 10, v2
	v_cndmask_b32_e64 v5, 0, 4, vcc
	v_cmp_gt_u32_e32 vcc, 16, v6
	v_add_u32_e32 v10, 11, v2
	v_mov_b32_e32 v11, 0x80
	v_cndmask_b32_e64 v6, 0, 8, vcc
	v_cmp_gt_u32_e32 vcc, 16, v7
	s_movk_i32 s6, 0xffef
	v_add_u32_e32 v12, 17, v2
	v_cndmask_b32_e64 v7, 0, 16, vcc
	v_cmp_gt_u32_e32 vcc, 16, v8
	v_mov_b32_e32 v13, 0x200
	v_mov_b32_e32 v14, 0x400
	v_cndmask_b32_e64 v8, 0, 32, vcc
	v_cmp_gt_u32_e32 vcc, 16, v9
	v_mov_b32_e32 v15, 0x800
	v_mov_b32_e32 v16, 0x1000
	v_cndmask_b32_e64 v9, 0, 64, vcc
	v_cmp_gt_u32_e32 vcc, 16, v10
	v_mov_b32_e32 v17, 0x2000
	v_mov_b32_e32 v18, 0x4000
	v_cndmask_b32_e32 v10, 0, v11, vcc
	v_mov_b32_e32 v11, 0x100
	v_cmp_lt_u32_e32 vcc, s6, v2
	s_add_i32 s8, 0, 0x11600
	v_readlane_b32 s95, v255, 18
	v_cndmask_b32_e32 v11, 0, v11, vcc
	v_cmp_gt_u32_e32 vcc, 16, v12
	v_or_b32_e32 v3, v11, v3
	v_or3_b32 v3, v3, v4, v5
	v_cndmask_b32_e32 v12, 0, v13, vcc
	v_add_u32_e32 v13, 18, v2
	v_cmp_gt_u32_e32 vcc, 16, v13
	v_or3_b32 v3, v3, v6, v7
	v_or3_b32 v3, v3, v8, v9
	v_cndmask_b32_e32 v13, 0, v14, vcc
	v_add_u32_e32 v14, 19, v2
	v_cmp_gt_u32_e32 vcc, 16, v14
	v_or3_b32 v3, v3, v10, v12
	v_lshl_add_u32 v151, v188, 2, s8
	v_cndmask_b32_e32 v14, 0, v15, vcc
	v_add_u32_e32 v15, 24, v2
	v_cmp_gt_u32_e32 vcc, 16, v15
	v_or3_b32 v3, v3, v13, v14
	s_lshr_b32 s8, s95, 8
	v_cndmask_b32_e32 v15, 0, v16, vcc
	v_add_u32_e32 v16, 25, v2
	v_cmp_gt_u32_e32 vcc, 16, v16
	s_mulk_i32 s8, 0xf8
	s_mov_b32 s4, 0x42400000
	v_cndmask_b32_e32 v16, 0, v17, vcc
	v_add_u32_e32 v17, 26, v2
	v_cmp_gt_u32_e32 vcc, 16, v17
	v_add_u32_e32 v2, 27, v2
	v_or3_b32 v3, v3, v15, v16
	v_cndmask_b32_e32 v17, 0, v18, vcc
	v_mov_b32_e32 v18, 0x8000
	v_cmp_gt_u32_e32 vcc, 16, v2
	s_movk_i32 s6, 0x1d1
	v_xor_b32_e32 v16, 0x80000000, v183
	v_cndmask_b32_e32 v2, 0, v18, vcc
	v_or3_b32 v150, v3, v17, v2
	v_add_u32_e32 v2, s3, v196
	v_mul_u32_u24_e32 v152, 0x90, v2
	v_or_b32_e32 v2, s3, v199
	v_lshlrev_b32_e32 v153, 6, v2
	v_sub_u32_e32 v2, s3, v0
	v_sub_u32_e32 v0, v198, v0
	v_subrev_u32_e32 v0, s2, v0
	v_subrev_u32_e32 v2, s2, v2
	v_lshlrev_b32_e32 v0, 2, v0
	v_lshl_add_u32 v2, v2, 2, v189
	v_lshl_add_u32 v0, s3, 2, v0
	v_subrev_u32_e32 v2, s8, v2
	v_subrev_u32_e32 v0, s8, v0
	v_add_u32_e32 v2, 0, v2
	v_add_u32_e32 v0, 0, v0
	v_readlane_b32 s92, v255, 9
	s_mov_b32 s43, 0
	v_cmp_ngt_f32_e64 s[4:5], s4, v183
	v_lshrrev_b32_e32 v148, 4, v196
	v_mov_b32_e32 v1, 0
	v_cmp_gt_i32_e64 s[6:7], s6, v188
	v_mov_b32_e32 v17, v16
	v_mov_b32_e32 v18, v16
	v_mov_b32_e32 v19, v16
	v_mov_b32_e32 v20, v16
	v_mov_b32_e32 v21, v16
	v_mov_b32_e32 v22, v16
	v_mov_b32_e32 v23, v16
	v_mov_b32_e32 v24, v16
	v_mov_b32_e32 v25, v16
	v_mov_b32_e32 v26, v16
	v_mov_b32_e32 v27, v16
	v_mov_b32_e32 v28, v16
	v_mov_b32_e32 v29, v16
	v_mov_b32_e32 v30, v16
	v_mov_b32_e32 v31, v16
	v_add_u32_e32 v154, 0x119a0, v2
	v_add_u32_e32 v155, 0x119a0, v0
	s_movk_i32 s2, 0x1200
	s_movk_i32 s3, 0xff84
	s_mov_b32 s46, 0xff800000
	v_mov_b32_e32 v156, 0x1200
	v_mov_b32_e32 v157, 0xff800000
	s_mov_b32 s47, 0
	v_readlane_b32 s89, v255, 14
	v_readlane_b32 s82, v255, 12
	v_readlane_b32 s83, v255, 11
	v_readlane_b32 s71, v255, 17
	v_readlane_b32 s93, v255, 10
	v_readlane_b32 s85, v255, 1
	v_readlane_b32 s56, v255, 0
	v_and_b32_e32 v212, 1, v150
	v_cmp_ne_u32_e32 vcc, 0, v212
	s_nop 1
	v_cndmask_b32_e32 v196, v157, v16, vcc
	v_and_b32_e32 v212, 2, v150
	v_cmp_ne_u32_e32 vcc, 0, v212
	s_nop 1
	v_cndmask_b32_e32 v197, v157, v17, vcc
	v_and_b32_e32 v212, 4, v150
	v_cmp_ne_u32_e32 vcc, 0, v212
	s_nop 1
	v_cndmask_b32_e32 v198, v157, v18, vcc
	v_and_b32_e32 v212, 8, v150
	v_cmp_ne_u32_e32 vcc, 0, v212
	s_nop 1
	v_cndmask_b32_e32 v199, v157, v19, vcc
	v_and_b32_e32 v212, 16, v150
	v_cmp_ne_u32_e32 vcc, 0, v212
	s_nop 1
	v_cndmask_b32_e32 v200, v157, v20, vcc
	v_and_b32_e32 v212, 32, v150
	v_cmp_ne_u32_e32 vcc, 0, v212
	s_nop 1
	v_cndmask_b32_e32 v201, v157, v21, vcc
	v_and_b32_e32 v212, 64, v150
	v_cmp_ne_u32_e32 vcc, 0, v212
	s_nop 1
	v_cndmask_b32_e32 v202, v157, v22, vcc
	v_and_b32_e32 v212, 0x80, v150
	v_cmp_ne_u32_e32 vcc, 0, v212
	s_nop 1
	v_cndmask_b32_e32 v203, v157, v23, vcc
	v_and_b32_e32 v212, 0x100, v150
	v_cmp_ne_u32_e32 vcc, 0, v212
	s_nop 1
	v_cndmask_b32_e32 v204, v157, v24, vcc
	v_and_b32_e32 v212, 0x200, v150
	v_cmp_ne_u32_e32 vcc, 0, v212
	s_nop 1
	v_cndmask_b32_e32 v205, v157, v25, vcc
	v_and_b32_e32 v212, 0x400, v150
	v_cmp_ne_u32_e32 vcc, 0, v212
	s_nop 1
	v_cndmask_b32_e32 v206, v157, v26, vcc
	v_and_b32_e32 v212, 0x800, v150
	v_cmp_ne_u32_e32 vcc, 0, v212
	s_nop 1
	v_cndmask_b32_e32 v207, v157, v27, vcc
	v_and_b32_e32 v212, 0x1000, v150
	v_cmp_ne_u32_e32 vcc, 0, v212
	s_nop 1
	v_cndmask_b32_e32 v208, v157, v28, vcc
	v_and_b32_e32 v212, 0x2000, v150
	v_cmp_ne_u32_e32 vcc, 0, v212
	s_nop 1
	v_cndmask_b32_e32 v209, v157, v29, vcc
	v_and_b32_e32 v212, 0x4000, v150
	v_cmp_ne_u32_e32 vcc, 0, v212
	s_nop 1
	v_cndmask_b32_e32 v210, v157, v30, vcc
	v_and_b32_e32 v212, 0x8000, v150
	v_cmp_ne_u32_e32 vcc, 0, v212
	s_nop 1
	v_cndmask_b32_e32 v211, v157, v31, vcc
	v_mov_b32_e32 v230, 0x13000
	v_and_b32_e32 v231, 31, v188
	v_lshl_add_u32 v231, v231, 2, v230
	ds_write_b32 v231, v157
	s_branch .LBB0_677

; #define LAS __attribute__((address_space(3)))
; template <int MASK, bool FIX> ...
;     const LAS unsigned char* kp = buf + (kvoff + r32) * KSTR + hi * 16;
;     f32x16 s = cinit;
; #pragma unroll
;     for (int d0 = 0; d0 < 4; ++d0) { const bf16x8 kf = *(const LAS bf16x8*)(kp + d0 * 32); s = __builtin_amdgcn_mfma_f32_32x32x16_bf16(kf, qf[d0], s, 0, 0, 0); }
;     const float NEG = -INFINITY;
;     if (MASK == 3) {
;         float bv[16];
; #pragma unroll
;         for (int r = 0; r < 16; ++r) bv[r] = rpbl[bidx0 + (r & 3) + 8 * (r >> 2)];
; #pragma unroll
;         for (int r = 0; r < 16; ++r) asm volatile("" : "+v"(bv[r]));
; #pragma unroll
;         for (int r = 0; r < 16; ++r) s[r] = ((vmask >> r) & 1u) ? (s[r] + bv[r]) : NEG;
;     }
; #pragma unroll
;     for (int r = 0; r < 16; ++r) {
;         const int kl0 = (r & 3) + 8 * (r >> 2);
;         if (MASK == 1) { if (kl0 + 4 * hi < r32) s[r] = NEG; }
;         if (MASK == 2) { if (kl0 + 4 * hi > r32) s[r] = NEG; }
;     }
;     if (!FIX) {
;         float mx = fmaxf(fmaxf(s[0], s[1]), fmaxf(s[2], s[3]));
; #pragma unroll
;         for (int r = 4; r < 16; r += 4) mx = fmaxf(mx, fmaxf(fmaxf(s[r], s[r + 1]), fmaxf(s[r + 2], s[r + 3])));
;         mx = swap_max(mx);
;         const float mnew = fmaxf(m, mx);
;         const float msafe = (mnew == NEG) ? 0.f : mnew;
;         if (__any(mnew > m)) {
;             const float alpha = __builtin_amdgcn_exp2f(m - msafe);
;             l *= alpha;
; #pragma unroll
;             for (int r = 0; r < 16; ++r) { o0[r] *= alpha; o1[r] *= alpha; }
;         }
;         m = mnew;
;         float ls = 0.f;
; #pragma unroll
;         for (int r = 0; r < 16; ++r) { s[r] = __builtin_amdgcn_exp2f(s[r] - msafe); ls += s[r]; }
;         l += ls;
;     } else {
; #pragma unroll
;         for (int r = 0; r < 16; ++r) s[r] = __builtin_amdgcn_exp2f(s[r]);
;         l += (((s[0] + s[1]) + (s[2] + s[3])) + ((s[4] + s[5]) + (s[6] + s[7]))) + (((s[8] + s[9]) + (s[10] + s[11])) + ((s[12] + s[13]) + (s[14] + s[15])));
;     }
;     u32x4 pw0, pw1;
;     pw0.x = cvtpk(s[0], s[1]); pw0.y = cvtpk(s[2], s[3]); pw0.z = cvtpk(s[4], s[5]); pw0.w = cvtpk(s[6], s[7]);
;     pw1.x = cvtpk(s[8], s[9]); pw1.y = cvtpk(s[10], s[11]); pw1.z = cvtpk(s[12], s[13]); pw1.w = cvtpk(s[14], s[15]);
;     const bf16x8 p0 = __builtin_bit_cast(bf16x8, pw0), p1 = __builtin_bit_cast(bf16x8, pw1);
.LBB0_727:
	s_bitcmp1_b32 s10, 0
	s_cselect_b32 s8, 0x4480, 0
	s_add_i32 s13, s48, s10
	v_add_u32_e32 v64, s10, v81
	s_add_i32 s55, s10, 1
	s_add_i32 s11, s54, s10
	s_add_i32 s14, s8, 0
	s_add_i32 s12, s13, 1
	v_cmp_gt_u32_e32 vcc, 8, v64
	v_cmp_lt_u32_e64 s[8:9], s13, v15
	s_cmp_lt_i32 s10, s49
	v_cndmask_b32_e32 v212, v230, v82, vcc
	v_cmp_gt_u32_e32 vcc, s13, v80
	s_cselect_b32 s10, s12, s11
	s_cselect_b32 s11, s51, s52
	s_and_b64 s[8:9], s[44:45], s[8:9]
	v_add_u32_e32 v65, s14, v178
	s_lshl_b32 s10, s10, 6
	s_or_b64 s[8:9], s[8:9], vcc
	v_add_u32_e32 v66, s14, v194
	s_waitcnt vmcnt(1)
	ds_write_b128 v65, v[96:99]
	s_waitcnt vmcnt(0)
	ds_write_b128 v66, v[100:103] offset:9216
	v_cndmask_b32_e64 v212, v212, v230, s[8:9]
	s_add_i32 s10, s10, s11
	v_add3_u32 v67, s14, v152, v189
	v_mad_i64_i32 v[240:241], s[8:9], s10, v156, v[104:105]
	s_nop 1
	global_load_dwordx4 v[96:99], v[240:241], off offset:2560
	global_load_dwordx4 v[100:103], v[240:241], off offset:3584
	s_waitcnt lgkmcnt(0)
	s_barrier
	ds_read_b128 v[84:87], v67
	ds_read_b128 v[88:91], v67 offset:32
	ds_read_b128 v[106:109], v67 offset:64
	ds_read_b128 v[110:113], v67 offset:96
	ds_read2_b32 v[118:119], v212 offset1:1
	ds_read2_b32 v[120:121], v212 offset0:2 offset1:3
	ds_read2_b32 v[122:123], v212 offset0:8 offset1:9
	ds_read2_b32 v[124:125], v212 offset0:10 offset1:11
	ds_read2_b32 v[126:127], v212 offset0:16 offset1:17
	ds_read2_b32 v[128:129], v212 offset0:18 offset1:19
	ds_read2_b32 v[130:131], v212 offset0:24 offset1:25
	s_waitcnt lgkmcnt(13)
	ds_read2_b32 v[132:133], v212 offset0:26 offset1:27
	v_add3_u32 v68, s14, v190, v153
	v_add3_u32 v83, v68, v191, v192
	s_waitcnt lgkmcnt(11)
	v_mfma_f32_32x32x16_bf16 v[64:79], v[84:87], v[2:5], v[196:211]
	s_waitcnt lgkmcnt(7)
	s_waitcnt lgkmcnt(6)
	s_waitcnt lgkmcnt(5)
	s_waitcnt lgkmcnt(4)
	v_mfma_f32_32x32x16_bf16 v[64:79], v[88:91], v[6:9], v[64:79]
	s_waitcnt lgkmcnt(3)
	s_waitcnt lgkmcnt(2)
	s_waitcnt lgkmcnt(1)
	v_mfma_f32_32x32x16_bf16 v[64:79], v[106:109], v[10:13], v[64:79]
	s_waitcnt lgkmcnt(0)
	ds_read_b64_tr_b16 v[84:85], v83 offset:9216
	v_mfma_f32_32x32x16_bf16 v[64:79], v[110:113], v[92:95], v[64:79]
	ds_read_b64_tr_b16 v[86:87], v83 offset:9728
	ds_read_b64_tr_b16 v[88:89], v83 offset:10240
	ds_read_b64_tr_b16 v[90:91], v83 offset:10752
	ds_read_b64_tr_b16 v[106:107], v83 offset:13376
	ds_read_b64_tr_b16 v[108:109], v83 offset:13888
	ds_read_b64_tr_b16 v[114:115], v83 offset:14400
	ds_read_b64_tr_b16 v[116:117], v83 offset:14912
	s_nop 5
	v_pk_add_f32 v[214:215], v[118:119], v[64:65]
	v_pk_add_f32 v[216:217], v[120:121], v[66:67]
	v_pk_add_f32 v[218:219], v[122:123], v[68:69]
	v_pk_add_f32 v[220:221], v[124:125], v[70:71]
	v_pk_add_f32 v[222:223], v[126:127], v[72:73]
	v_pk_add_f32 v[224:225], v[128:129], v[74:75]
	v_pk_add_f32 v[226:227], v[130:131], v[76:77]
	v_pk_add_f32 v[228:229], v[132:133], v[78:79]
	v_exp_f32_e32 v68, v214
	v_exp_f32_e32 v70, v215
	v_exp_f32_e32 v72, v216
	v_exp_f32_e32 v74, v217
	v_exp_f32_e32 v76, v218
	v_exp_f32_e32 v78, v219
	v_exp_f32_e32 v110, v220
	v_exp_f32_e32 v112, v221
	v_cvt_pk_bf16_f32 v64, v68, v70
	v_cvt_pk_bf16_f32 v65, v72, v74
	v_cvt_pk_bf16_f32 v66, v76, v78
	v_cvt_pk_bf16_f32 v67, v110, v112
	s_nop 0
	s_waitcnt lgkmcnt(6)
	v_mfma_f32_32x32x16_bf16 v[32:47], v[84:87], v[64:67], v[32:47]
	s_waitcnt lgkmcnt(2)
	v_mfma_f32_32x32x16_bf16 v[48:63], v[106:109], v[64:67], v[48:63]
	v_exp_f32_e32 v69, v222
	v_exp_f32_e32 v71, v223
	v_exp_f32_e32 v73, v224
	v_exp_f32_e32 v75, v225
	v_exp_f32_e32 v77, v226
	v_exp_f32_e32 v79, v227
	v_exp_f32_e32 v111, v228
	v_exp_f32_e32 v113, v229
	v_cvt_pk_bf16_f32 v64, v69, v71
	v_cvt_pk_bf16_f32 v65, v73, v75
	v_cvt_pk_bf16_f32 v66, v77, v79
	v_cvt_pk_bf16_f32 v67, v111, v113
	v_pk_add_f32 v[68:69], v[68:69], v[70:71]
	v_pk_add_f32 v[72:73], v[72:73], v[74:75]
	v_mfma_f32_32x32x16_bf16 v[32:47], v[88:91], v[64:67], v[32:47]
	v_pk_add_f32 v[76:77], v[76:77], v[78:79]
	v_pk_add_f32 v[110:111], v[110:111], v[112:113]
	s_mov_b32 s10, s55
	v_add_u32_e32 v82, 0x7c, v82
	s_cmp_eq_u32 s42, s55
	s_waitcnt lgkmcnt(0)
	v_mfma_f32_32x32x16_bf16 v[48:63], v[114:117], v[64:67], v[48:63]
	v_pk_add_f32 v[68:69], v[68:69], v[72:73]
	v_pk_add_f32 v[76:77], v[76:77], v[110:111]
	s_nop 0
	v_pk_add_f32 v[68:69], v[68:69], v[76:77]
	s_nop 0
	v_add_f32_e32 v64, v68, v69
	v_add_f32_e32 v0, v0, v64
	s_cbranch_scc0 .LBB0_727
	s_add_i32 s11, s49, 1
	s_branch .LBB0_730
